# v7 plus GLA head-norm gain load no longer waited before the chunk prefetches are issued
# baseline (speedup 1.0000x reference)
; template <bool FULL> __device__ __forceinline__ void gla_unit(LAS unsigned char* lds, const MixBufs& B, int b, int h, int seg, int tid) {
;     ...
;     if (FULL) { if (tid < 128) GNL[tid] = B.g_gla_norm[tid]; }
;     v4u rq[3], rk[3], rv0[3], rv1[3], re[3]; float rdl[3] = {0.f, 0.f, 0.f}; u32x2 gvp[3][4];
;     ...
;     GLA_PREFETCH(0, 8 * seg); GLA_PREFETCH(1, 8 * seg + 1); GLA_PREFETCH(2, 8 * seg + 2);
.LBB0_684:
	s_movk_i32 s23, 0x90
	v_cmp_gt_i32_e32 vcc, s69, v134
	v_ashrrev_i32_e32 v135, 31, v134
	v_lshl_add_u32 v178, v134, 2, 0
	s_and_saveexec_b64 s[2:3], vcc
	s_cbranch_execz .LBB0_686
	v_lshl_add_u64 v[4:5], v[134:135], 2, s[62:63]
	global_load_dword v220, v[4:5], off
	v_add_u32_e32 v221, 0x16d00, v178
	s_nop 0
	s_nop 0

; #define LAS __attribute__((address_space(3)))
; __device__ __forceinline__ float bflo(unsigned w) { return __uint_as_float(w << 16); }
; __device__ __forceinline__ float bfhi(unsigned w) { return __uint_as_float(w & 0xffff0000u); }
; __device__ __forceinline__ u32x2 f32_to_bf4(f32x4 v) { u32x2 w; w.x = cvtpk(v[0], v[1]); w.y = cvtpk(v[2], v[3]); return w; }
; template <bool FULL> __device__ __forceinline__ void gla_unit(LAS unsigned char* lds, const MixBufs& B, int b, int h, int seg, int tid) {
;     ...
;     GLA_PREFETCH(0, 8 * seg); GLA_PREFETCH(1, 8 * seg + 1); GLA_PREFETCH(2, 8 * seg + 2);
; #pragma unroll
;     for (int ci = 0; ci < 8; ++ci) {
;         const int ch = 8 * seg + ci, st = ci % 3;
;         const size_t t0 = (size_t)b * T + (size_t)ch * CH;
;         const int okf = (ci & 1) ? G_KF2 : G_KF; LAS float* DLc = (ci & 1) ? (LAS float*)(lds + G_DL2) : DL;
;         const int ov = (!FULL && (ci & 1)) ? G_ST : G_V;
;         { const v4u ee = re[st]; const f32x4 e0 = (f32x4){bflo(ee.x), bfhi(ee.x), bflo(ee.y), bfhi(ee.y)}, e1 = (f32x4){bflo(ee.z), bfhi(ee.z), bflo(ee.w), bfhi(ee.w)};
;           f32x4 i0, i1;
; #pragma unroll
;           for (int e = 0; e < 4; ++e) { i0[e] = __builtin_amdgcn_rcpf(e0[e]); i1[e] = __builtin_amdgcn_rcpf(e1[e]); }
;           *(LAS v4u*)(lds + okf + lr * GP64 + lc * 16) = mul_bf8(rk[st], i0, i1);
;           if (FULL) { *(LAS v4u*)(lds + G_KB + lr * GP64 + lc * 16) = mul_bf8(rk[st], e0, e1);
;                       *(LAS v4u*)(lds + G_QF + lr * GP64 + lc * 16) = mul_bf8(rq[st], e0, e1); *(LAS v4u*)(lds + G_QB + lr * GP64 + lc * 16) = mul_bf8(rq[st], i0, i1); } }
;         *(LAS v4u*)(lds + ov + vr * GP128 + vc * 16) = rv0[st]; *(LAS v4u*)(lds + ov + (vr + 32) * GP128 + vc * 16) = rv1[st];
;         if (tid < 64) DLc[tid] = rdl[st];
;         if (FULL) {
; #pragma unroll
;             for (int j = 0; j < 4; ++j) *(LAS u32x2*)(lds + G_ST + (16 * (4 * vh + j) + c) * GP64 + (16 * kt + 4 * g) * 2) = f32_to_bf4(S[j]);
;         }
;         const size_t trow = t0 + 16 * ti + c;
;         u32x2 gv[4];
;         if (FULL) {
; #pragma unroll
;             for (int j = 0; j < 4; ++j) gv[j] = gvp[st][j];
;         }
;         if (ci + 3 < 8) GLA_PREFETCH(st, ch + 3);
.LBB0_696:
	s_or_b64 exec, exec, s[4:5]
	v_or_b32_e32 v85, s6, v122
	v_mov_b64_e32 v[86:87], s[52:53]
	s_mul_i32 s6, s7, 0x2600
	v_mad_u64_u32 v[86:87], s[4:5], v85, s33, v[86:87]
	v_add_u32_e32 v87, s6, v87
	v_lshl_add_u64 v[86:87], v[86:87], 0, s[8:9]
	v_mov_b32_e32 v133, v3
	v_lshl_add_u64 v[86:87], v[86:87], 0, v[132:133]
	v_lshl_add_u64 v[86:87], s[60:61], 1, v[86:87]
	global_load_dwordx2 v[168:169], v[86:87], off offset:2048
	global_load_dwordx2 v[160:161], v[86:87], off offset:2080
	global_load_dwordx2 v[130:131], v[86:87], off offset:2112
	global_load_dwordx2 v[128:129], v[86:87], off offset:2144
	v_mul_lo_u32 v147, v138, s23
	s_waitcnt vmcnt(24)
	v_lshlrev_b32_e32 v92, 16, v20
	v_and_b32_e32 v93, 0xffff0000, v20
	v_add_u32_e32 v85, 0, v147
	v_rcp_f32_e32 v94, v92
	v_rcp_f32_e32 v95, v93
	v_add_u32_e32 v180, v85, v146
	v_mul_lo_u32 v85, v136, s75
	v_add_u32_e32 v85, 0, v85
	v_add_u32_e32 v181, v85, v84
	v_lshlrev_b32_e32 v84, 16, v52
	v_and_b32_e32 v85, 0xffff0000, v52
	v_lshlrev_b32_e32 v86, 16, v53
	v_and_b32_e32 v87, 0xffff0000, v53
	v_pk_mul_f32 v[52:53], v[94:95], v[84:85]
	v_lshlrev_b32_e32 v88, 16, v54
	v_cvt_pk_bf16_f32 v20, v52, v53
	v_pk_mul_f32 v[52:53], v[84:85], v[92:93]
	v_lshlrev_b32_e32 v84, 16, v21
	v_and_b32_e32 v85, 0xffff0000, v21
	v_rcp_f32_e32 v96, v84
	v_rcp_f32_e32 v97, v85
	v_and_b32_e32 v89, 0xffff0000, v54
	v_lshlrev_b32_e32 v90, 16, v55
	v_and_b32_e32 v91, 0xffff0000, v55
	v_pk_mul_f32 v[54:55], v[96:97], v[86:87]
	v_cvt_pk_bf16_f32 v52, v52, v53
	v_cvt_pk_bf16_f32 v21, v54, v55
	v_pk_mul_f32 v[54:55], v[86:87], v[84:85]
	v_lshlrev_b32_e32 v86, 16, v22
	v_and_b32_e32 v87, 0xffff0000, v22
	v_rcp_f32_e32 v98, v86
	v_rcp_f32_e32 v99, v87
	v_cvt_pk_bf16_f32 v53, v54, v55
	v_pk_mul_f32 v[54:55], v[98:99], v[88:89]
	s_nop 0
	v_cvt_pk_bf16_f32 v22, v54, v55
	v_pk_mul_f32 v[54:55], v[88:89], v[86:87]
	v_lshlrev_b32_e32 v88, 16, v23
	v_and_b32_e32 v89, 0xffff0000, v23
	v_rcp_f32_e32 v100, v88
	v_rcp_f32_e32 v101, v89
	v_cvt_pk_bf16_f32 v54, v54, v55
	v_pk_mul_f32 v[102:103], v[100:101], v[90:91]
	s_nop 0
	v_cvt_pk_bf16_f32 v23, v102, v103
	ds_write_b128 v180, v[20:23] offset:18432
	v_pk_mul_f32 v[20:21], v[90:91], v[88:89]
	s_nop 0
	v_cvt_pk_bf16_f32 v55, v20, v21
	v_lshlrev_b32_e32 v20, 16, v4
	v_and_b32_e32 v21, 0xffff0000, v4
	v_pk_mul_f32 v[22:23], v[20:21], v[92:93]
	ds_write_b128 v180, v[52:55] offset:27648
	v_cvt_pk_bf16_f32 v4, v22, v23
	v_lshlrev_b32_e32 v22, 16, v5
	v_and_b32_e32 v23, 0xffff0000, v5
	v_pk_mul_f32 v[52:53], v[22:23], v[84:85]
	s_nop 0
	v_cvt_pk_bf16_f32 v5, v52, v53
	v_lshlrev_b32_e32 v52, 16, v6
	v_and_b32_e32 v53, 0xffff0000, v6
	v_pk_mul_f32 v[54:55], v[52:53], v[86:87]
	s_nop 0
	v_cvt_pk_bf16_f32 v6, v54, v55
	v_lshlrev_b32_e32 v54, 16, v7
	v_and_b32_e32 v55, 0xffff0000, v7
	v_pk_mul_f32 v[84:85], v[54:55], v[88:89]
	s_nop 0
	v_cvt_pk_bf16_f32 v7, v84, v85
	ds_write_b128 v180, v[4:7]
	v_pk_mul_f32 v[4:5], v[94:95], v[20:21]
	v_pk_mul_f32 v[6:7], v[96:97], v[22:23]
	v_cvt_pk_bf16_f32 v4, v4, v5
	v_cvt_pk_bf16_f32 v5, v6, v7
	v_pk_mul_f32 v[6:7], v[98:99], v[52:53]
	v_pk_mul_f32 v[20:21], v[100:101], v[54:55]
	v_cvt_pk_bf16_f32 v6, v6, v7
	v_cvt_pk_bf16_f32 v7, v20, v21
	ds_write_b128 v180, v[4:7] offset:9216
	s_waitcnt vmcnt(23)
	ds_write_b128 v181, v[8:11] offset:36864
	s_waitcnt vmcnt(22)
	ds_write_b128 v181, v[12:15] offset:45568
	s_and_saveexec_b64 s[4:5], s[2:3]
	v_add_u32_e32 v4, 0x14000, v178
	ds_write_b32 v4, v202
	s_or_b64 exec, exec, s[4:5]
	v_cmp_gt_i32_e64 s[100:101], s69, v134
	s_nop 1
	s_and_saveexec_b64 s[4:5], s[100:101]
	ds_write_b32 v221, v220
	s_or_b64 exec, exec, s[4:5]
	s_lshl_b32 s4, s20, 5
	v_or_b32_e32 v6, s60, v177
	s_add_i32 s4, s4, 0
	v_add_u32_e32 v7, s4, v120
	v_mul_lo_u32 v124, v6, s23
	v_cvt_pk_bf16_f32 v4, v40, v41
	v_cvt_pk_bf16_f32 v5, v42, v43
	v_add_u32_e32 v185, v7, v124
	v_add_u32_e32 v121, 0x900, v124
	ds_write_b64 v185, v[4:5] offset:63488
	v_cvt_pk_bf16_f32 v4, v36, v37
	v_cvt_pk_bf16_f32 v5, v38, v39
	v_add_u32_e32 v186, v7, v121
	v_add_u32_e32 v123, 0x1200, v124
	s_or_b32 s10, s80, 3
	ds_write_b64 v186, v[4:5] offset:63488
	v_cvt_pk_bf16_f32 v4, v32, v33
	v_cvt_pk_bf16_f32 v5, v34, v35
	v_add_u32_e32 v187, v7, v123
	v_add_u32_e32 v153, 0x1b00, v124
	s_lshl_b32 s4, s10, 6
	ds_write_b64 v187, v[4:5] offset:63488
	v_cvt_pk_bf16_f32 v4, v80, v81
	v_cvt_pk_bf16_f32 v5, v82, v83
	v_add_u32_e32 v188, v7, v153
	s_or_b32 s4, s90, s4
	s_mov_b32 s5, s91
	ds_write_b64 v188, v[4:5] offset:63488
	v_lshl_add_u64 v[4:5], s[4:5], 0, v[138:139]
	v_mov_b64_e32 v[6:7], s[52:53]
	v_mad_u64_u32 v[8:9], s[6:7], v4, s33, v[6:7]
	v_mad_i32_i24 v9, v5, s33, v9
	v_lshlrev_b64 v[4:5], 9, v[4:5]
	s_mov_b32 s77, s9
	v_lshl_add_u64 v[4:5], s[94:95], 0, v[4:5]
	v_lshl_add_u64 v[8:9], v[8:9], 0, s[76:77]
	v_lshl_add_u64 v[4:5], v[4:5], 0, s[76:77]
	v_lshl_add_u64 v[12:13], v[8:9], 0, v[2:3]
	v_lshl_add_u64 v[4:5], v[4:5], 0, v[2:3]
	global_load_dwordx4 v[8:11], v[12:13], off nt
	global_load_dwordx4 v[52:55], v[12:13], off offset:512 nt
	global_load_dwordx4 v[20:23], v[4:5], off nt
	v_lshl_add_u64 v[4:5], s[4:5], 0, v[136:137]
	v_mad_u64_u32 v[6:7], s[6:7], v4, s33, v[6:7]
	v_mad_i32_i24 v7, v5, s33, v7
	v_lshl_add_u64 v[4:5], v[6:7], 0, s[8:9]
	v_mov_b32_e32 v143, v3
	v_lshl_add_u64 v[12:13], v[4:5], 0, v[142:143]
	global_load_dwordx4 v[4:7], v[12:13], off offset:1024 nt
	v_add_co_u32_e32 v12, vcc, 0x4c000, v12
	s_nop 1
	v_addc_co_u32_e32 v13, vcc, 0, v13, vcc
	global_load_dwordx4 v[12:15], v[12:13], off offset:1024 nt
	s_and_saveexec_b64 s[6:7], s[2:3]
	s_cbranch_execz .LBB0_700
	s_lshl_b32 s10, s10, 10
	s_mov_b32 s11, s9
	v_lshl_add_u64 v[80:81], v[140:141], 0, s[10:11]
	s_lshl_b32 s10, s78, 2
	v_lshl_add_u64 v[80:81], v[80:81], 0, s[10:11]
	v_lshl_add_u64 v[80:81], v[134:135], 2, v[80:81]
	global_load_dword v202, v[80:81], off
